# attention deferred-rescale threshold raised from 2^12 to 2^24 (fewer rescale passes; f32 range unaffected)
# speedup vs baseline: 1.0053x; 1.0053x over previous
.Lat_nomask_526:
	ds_read_b64_tr_b16 v[200:201], v250 offset:8192
	ds_read_b64_tr_b16 v[202:203], v250 offset:8704
	ds_read_b64_tr_b16 v[204:205], v250 offset:12288
	ds_read_b64_tr_b16 v[206:207], v250 offset:12800
	s_waitcnt lgkmcnt(4)
	v_mfma_f32_32x32x16_bf16 v[32:47], v[176:179], v[192:195], v[32:47]
	v_max3_f32 v2, v128, v129, v144
	v_max3_f32 v4, v130, v131, v145
	v_max3_f32 v2, v2, v146, v147
	v_mfma_f32_32x32x16_bf16 v[48:63], v[176:179], v[196:199], v[48:63]
	v_max3_f32 v2, v2, v132, v133
	v_max3_f32 v4, v4, v134, v135
	v_max3_f32 v2, v2, v148, v149
	ds_read_b64_tr_b16 v[192:193], v250 offset:1024
	ds_read_b64_tr_b16 v[194:195], v250 offset:1536
	ds_read_b64_tr_b16 v[196:197], v250 offset:5120
	ds_read_b64_tr_b16 v[198:199], v250 offset:5632
	s_waitcnt lgkmcnt(4)
	v_mfma_f32_32x32x16_bf16 v[64:79], v[176:179], v[200:203], v[64:79]
	v_max3_f32 v4, v4, v150, v151
	v_max3_f32 v2, v2, v136, v137
	v_max3_f32 v4, v4, v138, v139
	v_mfma_f32_32x32x16_bf16 v[80:95], v[176:179], v[204:207], v[80:95]
	v_max3_f32 v2, v2, v152, v153
	v_max3_f32 v4, v4, v154, v155
	v_max3_f32 v2, v2, v140, v141
	ds_read_b64_tr_b16 v[200:201], v250 offset:9216
	ds_read_b64_tr_b16 v[202:203], v250 offset:9728
	ds_read_b64_tr_b16 v[204:205], v250 offset:13312
	ds_read_b64_tr_b16 v[206:207], v250 offset:13824
	s_waitcnt lgkmcnt(4)
	v_mfma_f32_32x32x16_bf16 v[32:47], v[180:183], v[192:195], v[32:47]
	v_max3_f32 v4, v4, v142, v143
	v_max3_f32 v2, v2, v156, v157
	v_max3_f32 v4, v4, v158, v159
	v_mfma_f32_32x32x16_bf16 v[48:63], v[180:183], v[196:199], v[48:63]
	v_max_f32_e32 v2, v2, v4
	v_mov_b32_e32 v4, v2
	s_nop 1
	v_permlane32_swap_b32_e32 v2, v4
	v_max_f32_e32 v2, v2, v4
	v_mov_b32_e32 v5, 0x41c00000
	v_cmp_gt_f32_e32 vcc, v2, v5
	s_mov_b64 s[68:69], vcc
	s_cmp_lg_u64 vcc, 0
	s_cbranch_scc0 .Lat_noresc_443
	v_max_f32_e32 v4, 0, v2
	v_add_f32_e32 v248, v248, v4
	v_sub_f32_e32 v128, v128, v4
	v_sub_f32_e32 v129, v129, v4
	v_sub_f32_e32 v130, v130, v4
	v_sub_f32_e32 v131, v131, v4
	v_sub_f32_e32 v132, v132, v4
	v_sub_f32_e32 v133, v133, v4
	v_sub_f32_e32 v134, v134, v4
	v_sub_f32_e32 v135, v135, v4
	v_sub_f32_e32 v136, v136, v4
	v_sub_f32_e32 v137, v137, v4
	v_sub_f32_e32 v138, v138, v4
	v_sub_f32_e32 v139, v139, v4
	v_sub_f32_e32 v140, v140, v4
	v_sub_f32_e32 v141, v141, v4
	v_sub_f32_e32 v142, v142, v4
	v_sub_f32_e32 v143, v143, v4
	v_sub_f32_e32 v144, v144, v4
	v_sub_f32_e32 v145, v145, v4
	v_sub_f32_e32 v146, v146, v4
	v_sub_f32_e32 v147, v147, v4
	v_sub_f32_e32 v148, v148, v4
	v_sub_f32_e32 v149, v149, v4
	v_sub_f32_e32 v150, v150, v4
	v_sub_f32_e32 v151, v151, v4
	v_sub_f32_e32 v152, v152, v4
	v_sub_f32_e32 v153, v153, v4
	v_sub_f32_e32 v154, v154, v4
	v_sub_f32_e32 v155, v155, v4
	v_sub_f32_e32 v156, v156, v4
	v_sub_f32_e32 v157, v157, v4
	v_sub_f32_e32 v158, v158, v4
	v_sub_f32_e32 v159, v159, v4
	v_xor_b32_e32 v5, 0x80000000, v248
	v_mov_b32_e32 v160, v5
	v_mov_b32_e32 v161, v5
	v_mov_b32_e32 v162, v5
	v_mov_b32_e32 v163, v5
	v_mov_b32_e32 v164, v5
	v_mov_b32_e32 v165, v5
	v_mov_b32_e32 v166, v5
	v_mov_b32_e32 v167, v5
	v_mov_b32_e32 v168, v5
	v_mov_b32_e32 v169, v5
	v_mov_b32_e32 v170, v5
	v_mov_b32_e32 v171, v5
	v_mov_b32_e32 v172, v5
	v_mov_b32_e32 v173, v5
	v_mov_b32_e32 v174, v5
	v_mov_b32_e32 v175, v5
	v_xor_b32_e32 v6, 0x80000000, v4
	v_exp_f32_e32 v6, v6
	s_nop 0
	v_mul_f32_e32 v247, v247, v6
	v_and_b32_e32 v7, 31, v237
	v_lshl_add_u32 v7, v7, 2, v249
	v_cmp_eq_u32_e32 vcc, 0, v252
	s_and_saveexec_b64 s[60:61], vcc
	ds_write_b32 v7, v6
	s_or_b64 exec, exec, s[60:61]

.Lat_nomask_945:
	ds_read_b64_tr_b16 v[200:201], v250 offset:8192
	ds_read_b64_tr_b16 v[202:203], v250 offset:8704
	ds_read_b64_tr_b16 v[204:205], v250 offset:12288
	ds_read_b64_tr_b16 v[206:207], v250 offset:12800
	s_waitcnt lgkmcnt(4)
	v_mfma_f32_32x32x16_bf16 v[32:47], v[176:179], v[192:195], v[32:47]
	v_max3_f32 v2, v96, v97, v112
	v_max3_f32 v4, v98, v99, v113
	v_max3_f32 v2, v2, v114, v115
	v_mfma_f32_32x32x16_bf16 v[48:63], v[176:179], v[196:199], v[48:63]
	v_max3_f32 v2, v2, v100, v101
	v_max3_f32 v4, v4, v102, v103
	v_max3_f32 v2, v2, v116, v117
	ds_read_b64_tr_b16 v[192:193], v250 offset:1024
	ds_read_b64_tr_b16 v[194:195], v250 offset:1536
	ds_read_b64_tr_b16 v[196:197], v250 offset:5120
	ds_read_b64_tr_b16 v[198:199], v250 offset:5632
	s_waitcnt lgkmcnt(4)
	v_mfma_f32_32x32x16_bf16 v[64:79], v[176:179], v[200:203], v[64:79]
	v_max3_f32 v4, v4, v118, v119
	v_max3_f32 v2, v2, v104, v105
	v_max3_f32 v4, v4, v106, v107
	v_mfma_f32_32x32x16_bf16 v[80:95], v[176:179], v[204:207], v[80:95]
	v_max3_f32 v2, v2, v120, v121
	v_max3_f32 v4, v4, v122, v123
	v_max3_f32 v2, v2, v108, v109
	ds_read_b64_tr_b16 v[200:201], v250 offset:9216
	ds_read_b64_tr_b16 v[202:203], v250 offset:9728
	ds_read_b64_tr_b16 v[204:205], v250 offset:13312
	ds_read_b64_tr_b16 v[206:207], v250 offset:13824
	s_waitcnt lgkmcnt(4)
	v_mfma_f32_32x32x16_bf16 v[32:47], v[180:183], v[192:195], v[32:47]
	v_max3_f32 v4, v4, v110, v111
	v_max3_f32 v2, v2, v124, v125
	v_max3_f32 v4, v4, v126, v127
	v_mfma_f32_32x32x16_bf16 v[48:63], v[180:183], v[196:199], v[48:63]
	v_max_f32_e32 v2, v2, v4
	v_mov_b32_e32 v4, v2
	s_nop 1
	v_permlane32_swap_b32_e32 v2, v4
	v_max_f32_e32 v2, v2, v4
	v_mov_b32_e32 v5, 0x41c00000
	v_cmp_gt_f32_e32 vcc, v2, v5
	s_mov_b64 s[68:69], vcc
	s_cmp_lg_u64 vcc, 0
	s_cbranch_scc0 .Lat_noresc_862
	v_max_f32_e32 v4, 0, v2
	v_add_f32_e32 v248, v248, v4
	v_sub_f32_e32 v96, v96, v4
	v_sub_f32_e32 v97, v97, v4
	v_sub_f32_e32 v98, v98, v4
	v_sub_f32_e32 v99, v99, v4
	v_sub_f32_e32 v100, v100, v4
	v_sub_f32_e32 v101, v101, v4
	v_sub_f32_e32 v102, v102, v4
	v_sub_f32_e32 v103, v103, v4
	v_sub_f32_e32 v104, v104, v4
	v_sub_f32_e32 v105, v105, v4
	v_sub_f32_e32 v106, v106, v4
	v_sub_f32_e32 v107, v107, v4
	v_sub_f32_e32 v108, v108, v4
	v_sub_f32_e32 v109, v109, v4
	v_sub_f32_e32 v110, v110, v4
	v_sub_f32_e32 v111, v111, v4
	v_sub_f32_e32 v112, v112, v4
	v_sub_f32_e32 v113, v113, v4
	v_sub_f32_e32 v114, v114, v4
	v_sub_f32_e32 v115, v115, v4
	v_sub_f32_e32 v116, v116, v4
	v_sub_f32_e32 v117, v117, v4
	v_sub_f32_e32 v118, v118, v4
	v_sub_f32_e32 v119, v119, v4
	v_sub_f32_e32 v120, v120, v4
	v_sub_f32_e32 v121, v121, v4
	v_sub_f32_e32 v122, v122, v4
	v_sub_f32_e32 v123, v123, v4
	v_sub_f32_e32 v124, v124, v4
	v_sub_f32_e32 v125, v125, v4
	v_sub_f32_e32 v126, v126, v4
	v_sub_f32_e32 v127, v127, v4
	v_xor_b32_e32 v5, 0x80000000, v248
	v_mov_b32_e32 v160, v5
	v_mov_b32_e32 v161, v5
	v_mov_b32_e32 v162, v5
	v_mov_b32_e32 v163, v5
	v_mov_b32_e32 v164, v5
	v_mov_b32_e32 v165, v5
	v_mov_b32_e32 v166, v5
	v_mov_b32_e32 v167, v5
	v_mov_b32_e32 v168, v5
	v_mov_b32_e32 v169, v5
	v_mov_b32_e32 v170, v5
	v_mov_b32_e32 v171, v5
	v_mov_b32_e32 v172, v5
	v_mov_b32_e32 v173, v5
	v_mov_b32_e32 v174, v5
	v_mov_b32_e32 v175, v5
	v_xor_b32_e32 v6, 0x80000000, v4
	v_exp_f32_e32 v6, v6
	s_nop 0
	v_mul_f32_e32 v247, v247, v6
	v_and_b32_e32 v7, 31, v237
	v_lshl_add_u32 v7, v7, 2, v249
	v_cmp_eq_u32_e32 vcc, 0, v252
	s_and_saveexec_b64 s[60:61], vcc
	ds_write_b32 v7, v6
	s_or_b64 exec, exec, s[60:61]
